# grid barrier: XCD leaders add to the monotonic cross-XCD counter without return and poll that counter directly (removes the last-arriver round trip and the separate release word)
# speedup vs baseline: 1.0108x; 1.0108x over previous
.LBB0_839:
	s_andn2_saveexec_b64 s[10:11], s[10:11]
	s_cbranch_execz .LBB0_859
	s_mov_b64 s[10:11], exec
	buffer_wbl2 sc1
	s_waitcnt lgkmcnt(0)
	s_waitcnt vmcnt(0)
	v_add_u32_e32 v4, 1, v0
	v_mul_lo_u32 v4, v4, v2
	v_readlane_b32 s10, v254, 25
	v_readlane_b32 s11, v254, 26
	v_mov_b32_e32 v3, 1
	s_nop 4
	global_atomic_add v1, v3, s[10:11]
	s_mov_b32 s20, 0
.Lmy_tpoll:
	global_load_dword v3, v1, s[10:11] sc1
	s_waitcnt vmcnt(0)
	v_cmp_ge_u32_e32 vcc, v3, v4
	s_cbranch_vccnz .Lmy_tdone
	s_sleep 1
	s_add_i32 s20, s20, 1
	s_cmp_lt_u32 s20, 0x4000
	s_cbranch_scc1 .Lmy_tpoll
.Lmy_tdone:
	s_mov_b64 s[10:11], exec
	v_mbcnt_lo_u32_b32 v0, s10, 0
	v_mbcnt_hi_u32_b32 v0, s11, v0
	v_cmp_eq_u32_e32 vcc, 0, v0
	s_waitcnt vmcnt(0)
	buffer_inv sc1
	s_and_saveexec_b64 s[22:23], vcc
	s_cbranch_execz .LBB0_858
	s_bcnt1_i32_b64 s10, s[10:11]
	v_mov_b32_e32 v0, s10
	global_atomic_add v1, v0, s[12:13]
